# SGU item: hoist 28 serialized global loads (row chunks, W frags, epilogue u/gate/bias) + attention epilogue gate loads issued together
# speedup vs baseline: 1.0241x; 1.0136x over previous
.LBB0_91:
	s_or_b64 exec, exec, s[0:1]
	v_mov_b32_e32 v1, s8
	s_waitcnt lgkmcnt(0)
	s_barrier
	ds_read_b32 v1, v1
	s_mov_b64 s[0:1], -1
	s_waitcnt lgkmcnt(0)
	v_readfirstlane_b32 s97, v1
	s_cmpk_gt_i32 s97, 0x207
	s_cbranch_scc1 .LBB0_86
	s_cmp_gt_i32 s97, 7
	s_cbranch_scc0 .LBB0_150
	s_cmp_gt_u32 s97, 39
	s_cbranch_scc0 .LBB0_145
	s_cmpk_gt_u32 s97, 0x127
	s_cbranch_scc0 .LBB0_109
	s_cmpk_gt_u32 s97, 0x167
	s_cbranch_scc0 .LBB0_97
	v_readlane_b32 s0, v246, 63
	s_add_i32 s0, s0, s97
	v_mov_b32_e32 v47, v149
	s_lshl_b32 s0, s0, 5
	s_and_b32 s12, s0, 0xff80
	v_ashrrev_i32_e32 v2, 1, v47
	s_and_b32 s13, s97, 3
	v_add_u32_e32 v2, s12, v2
	v_mov_b64_e32 v[34:35], s[34:35]
	v_lshlrev_b32_e32 v4, 5, v47
	v_mad_i64_i32 v[2:3], s[0:1], v2, s9, v[34:35]
	s_lshl_b32 s2, s13, 7
	v_and_b32_e32 v17, 32, v4
	v_lshl_add_u64 v[2:3], v[2:3], 0, s[2:3]
	v_lshlrev_b32_e32 v4, 1, v17
	v_mov_b32_e32 v5, v0
	v_lshl_add_u64 v[8:9], v[2:3], 0, v[4:5]
	global_load_dwordx4 v[4:7], v[8:9], off offset:3072
	global_load_dwordx4 v[28:31], v[8:9], off offset:3120
	global_load_dwordx4 v[252:255], v[8:9], off offset:3088
	global_load_dwordx4 v[92:95], v[8:9], off offset:3104
	s_lshl_b32 s0, s13, 8
	v_readlane_b32 s1, v246, 30
	s_add_u32 s40, s1, s0
	v_readlane_b32 s1, v246, 31
	s_addc_u32 s41, s1, 0
	v_readlane_b32 s1, v246, 32
	s_add_u32 s0, s1, s0
	v_readlane_b32 s1, v246, 33
	s_addc_u32 s1, s1, 0
	v_readlane_b32 s42, v248, 7
	v_readlane_b32 s43, v248, 8
	v_and_b32_e32 v46, 15, v47
	v_ashrrev_i32_e32 v1, 6, v47
	v_readlane_b32 s60, v246, 5
	v_readlane_b32 s74, v246, 19
	v_readlane_b32 s75, v246, 20
	v_readlane_b32 s64, v246, 9
	v_readlane_b32 s65, v246, 10
	v_readlane_b32 s66, v246, 11
	v_readlane_b32 s67, v246, 12
	v_readlane_b32 s68, v246, 13
	v_readlane_b32 s69, v246, 14
	v_readlane_b32 s70, v246, 15
	v_readlane_b32 s71, v246, 16
	v_readlane_b32 s72, v246, 17
	v_readlane_b32 s73, v246, 18
	v_readlane_b32 s61, v246, 6
	v_readlane_b32 s62, v246, 7
	v_readlane_b32 s63, v246, 8
	s_waitcnt vmcnt(3)
	v_lshlrev_b32_e32 v2, 16, v4
	v_and_b32_e32 v20, 0xffff0000, v4
	v_lshlrev_b32_e32 v18, 16, v5
	v_and_b32_e32 v15, 0xffff0000, v5
	v_lshlrev_b32_e32 v13, 16, v6
	v_and_b32_e32 v12, 0xffff0000, v6
	v_lshlrev_b32_e32 v11, 16, v7
	v_and_b32_e32 v10, 0xffff0000, v7
	s_waitcnt vmcnt(1)
	v_mov_b32_e32 v4, v252
	v_mov_b32_e32 v5, v253
	v_mov_b32_e32 v6, v254
	v_mov_b32_e32 v7, v255
	v_add_f32_e32 v3, 0, v2
	v_add_f32_e32 v3, v3, v20
	v_add_f32_e32 v3, v3, v18
	v_add_f32_e32 v3, v3, v15
	v_add_f32_e32 v3, v3, v13
	v_add_f32_e32 v3, v3, v12
	v_add_f32_e32 v3, v3, v11
	v_add_f32_e32 v3, v3, v10
	s_waitcnt vmcnt(0)
	v_lshlrev_b32_e32 v25, 16, v4
	v_and_b32_e32 v24, 0xffff0000, v4
	v_lshlrev_b32_e32 v23, 16, v5
	v_and_b32_e32 v22, 0xffff0000, v5
	v_lshlrev_b32_e32 v21, 16, v6
	v_and_b32_e32 v19, 0xffff0000, v6
	v_lshlrev_b32_e32 v16, 16, v7
	v_and_b32_e32 v14, 0xffff0000, v7
	v_mov_b32_e32 v4, v92
	v_mov_b32_e32 v5, v93
	v_mov_b32_e32 v6, v94
	v_mov_b32_e32 v7, v95
	v_add_f32_e32 v3, v3, v25
	v_add_f32_e32 v3, v3, v24
	v_add_f32_e32 v3, v3, v23
	v_add_f32_e32 v3, v3, v22
	v_add_f32_e32 v3, v3, v21
	v_add_f32_e32 v3, v3, v19
	v_add_f32_e32 v3, v3, v16
	v_add_f32_e32 v3, v3, v14
	v_and_b32_e32 v9, 0xffff0000, v30
	v_lshlrev_b32_e32 v8, 16, v30
	v_lshlrev_b32_e32 v30, 16, v29
	s_waitcnt vmcnt(0)
	v_lshlrev_b32_e32 v26, 16, v4
	v_and_b32_e32 v52, 0xffff0000, v4
	v_add_f32_e32 v3, v3, v26
	v_lshlrev_b32_e32 v51, 16, v5
	v_add_f32_e32 v3, v3, v52
	v_and_b32_e32 v50, 0xffff0000, v5
	v_add_f32_e32 v3, v3, v51
	v_lshlrev_b32_e32 v49, 16, v6
	v_add_f32_e32 v3, v3, v50
	v_and_b32_e32 v5, 64, v223
	v_and_b32_e32 v48, 0xffff0000, v6
	v_add_f32_e32 v3, v3, v49
	v_xor_b32_e32 v4, 1, v223
	v_add_u32_e32 v5, 64, v5
	v_add_f32_e32 v3, v3, v48
	v_cmp_lt_i32_e32 vcc, v4, v5
	v_lshlrev_b32_e32 v32, 16, v7
	v_and_b32_e32 v33, 0xffff0000, v7
	v_cndmask_b32_e32 v4, v223, v4, vcc
	v_add_f32_e32 v3, v3, v32
	v_lshlrev_b32_e32 v27, 2, v4
	v_and_b32_e32 v5, 0xffff0000, v31
	v_lshlrev_b32_e32 v4, 16, v31
	v_and_b32_e32 v31, 0xffff0000, v29
	v_and_b32_e32 v29, 0xffff0000, v28
	v_lshlrev_b32_e32 v28, 16, v28
	v_add_f32_e32 v3, v3, v33
	v_add_f32_e32 v3, v3, v28
	v_add_f32_e32 v3, v3, v29
	v_add_f32_e32 v3, v3, v30
	v_add_f32_e32 v3, v3, v31
	v_add_f32_e32 v3, v3, v8
	v_add_f32_e32 v3, v3, v9
	v_add_f32_e32 v3, v3, v4
	v_add_f32_e32 v3, v3, v5
	ds_bpermute_b32 v6, v27, v3
	s_waitcnt lgkmcnt(0)
	v_add_f32_e32 v3, v3, v6
	v_fmac_f32_e32 v20, 0xbc800000, v3
	v_fmac_f32_e32 v2, 0xbc800000, v3
	v_mul_f32_e32 v7, v20, v20
	v_fmac_f32_e32 v7, v2, v2
	v_fmac_f32_e32 v18, 0xbc800000, v3
	v_fmac_f32_e32 v7, v18, v18
	v_fmac_f32_e32 v15, 0xbc800000, v3
	v_fmac_f32_e32 v7, v15, v15
	v_fmac_f32_e32 v13, 0xbc800000, v3
	v_fmac_f32_e32 v7, v13, v13
	v_fmac_f32_e32 v12, 0xbc800000, v3
	v_fmac_f32_e32 v7, v12, v12
	v_fmac_f32_e32 v11, 0xbc800000, v3
	v_fmac_f32_e32 v7, v11, v11
	v_fmac_f32_e32 v10, 0xbc800000, v3
	v_fmac_f32_e32 v7, v10, v10
	v_fmac_f32_e32 v25, 0xbc800000, v3
	v_fmac_f32_e32 v7, v25, v25
	v_fmac_f32_e32 v24, 0xbc800000, v3
	v_fmac_f32_e32 v7, v24, v24
	v_fmac_f32_e32 v23, 0xbc800000, v3
	v_fmac_f32_e32 v7, v23, v23
	v_fmac_f32_e32 v22, 0xbc800000, v3
	v_fmac_f32_e32 v7, v22, v22
	v_fmac_f32_e32 v21, 0xbc800000, v3
	v_fmac_f32_e32 v7, v21, v21
	v_fmac_f32_e32 v19, 0xbc800000, v3
	v_fmac_f32_e32 v7, v19, v19
	v_fmac_f32_e32 v16, 0xbc800000, v3
	v_fmac_f32_e32 v7, v16, v16
	v_fmac_f32_e32 v14, 0xbc800000, v3
	v_fmac_f32_e32 v7, v14, v14
	v_fmac_f32_e32 v26, 0xbc800000, v3
	v_fmac_f32_e32 v7, v26, v26
	v_fmac_f32_e32 v52, 0xbc800000, v3
	v_fmac_f32_e32 v7, v52, v52
	v_fmac_f32_e32 v51, 0xbc800000, v3
	v_fmac_f32_e32 v7, v51, v51
	v_fmac_f32_e32 v50, 0xbc800000, v3
	v_fmac_f32_e32 v7, v50, v50
	v_fmac_f32_e32 v49, 0xbc800000, v3
	v_fmac_f32_e32 v7, v49, v49
	v_fmac_f32_e32 v48, 0xbc800000, v3
	v_mul_f32_e32 v6, 0x3c800000, v3
	v_fmac_f32_e32 v7, v48, v48
	v_pk_add_f32 v[44:45], v[32:33], v[6:7] op_sel_hi:[1,0] neg_lo:[0,1] neg_hi:[0,1]
	v_pk_add_f32 v[42:43], v[28:29], v[6:7] op_sel_hi:[1,0] neg_lo:[0,1] neg_hi:[0,1]
	v_pk_mul_f32 v[32:33], v[44:45], v[44:45]
	v_pk_mul_f32 v[28:29], v[42:43], v[42:43]
	v_add_f32_e32 v3, v32, v7
	v_add_f32_e32 v3, v33, v3
	v_add_f32_e32 v3, v28, v3
	v_pk_add_f32 v[40:41], v[30:31], v[6:7] op_sel_hi:[1,0] neg_lo:[0,1] neg_hi:[0,1]
	v_add_f32_e32 v3, v29, v3
	v_pk_mul_f32 v[28:29], v[40:41], v[40:41]
	v_pk_add_f32 v[38:39], v[8:9], v[6:7] op_sel_hi:[1,0] neg_lo:[0,1] neg_hi:[0,1]
	v_add_f32_e32 v3, v28, v3
	v_add_f32_e32 v3, v29, v3
	v_pk_mul_f32 v[8:9], v[38:39], v[38:39]
	v_pk_add_f32 v[36:37], v[4:5], v[6:7] op_sel_hi:[1,0] neg_lo:[0,1] neg_hi:[0,1]
	v_add_f32_e32 v3, v8, v3
	v_add_f32_e32 v3, v9, v3
	v_pk_mul_f32 v[4:5], v[36:37], v[36:37]
	v_lshlrev_b32_e32 v30, 2, v17
	v_add_f32_e32 v3, v4, v3
	v_add_f32_e32 v3, v5, v3
	ds_bpermute_b32 v4, v27, v3
	v_and_b32_e32 v27, -2, v47
	v_mul_u32_u24_e32 v17, 0x110, v17
	v_add3_u32 v54, 0, v27, v17
	s_waitcnt lgkmcnt(0)
	v_add_f32_e32 v3, v3, v4
	v_fmamk_f32 v3, v3, 0x3c800000, v148
	v_cmp_gt_f32_e32 vcc, s98, v3
	v_mul_f32_e32 v4, 0x4b800000, v3
	s_nop 0
	v_cndmask_b32_e32 v3, v3, v4, vcc
	v_rsq_f32_e32 v3, v3
	s_nop 0
	v_mul_f32_e32 v4, 0x45800000, v3
	v_cndmask_b32_e32 v53, v3, v4, vcc
	v_mul_f32_e32 v28, v2, v53
	global_load_dwordx4 v[2:5], v30, s[40:41] offset:48
	global_load_dwordx4 v[6:9], v30, s[40:41] offset:32
	global_load_dwordx4 v[56:59], v30, s[40:41] offset:16
	global_load_dwordx4 v[60:63], v30, s[40:41]
	global_load_dwordx4 v[64:67], v30, s[0:1] offset:48
	global_load_dwordx4 v[68:71], v30, s[0:1] offset:32
	global_load_dwordx4 v[72:75], v30, s[0:1] offset:16
	global_load_dwordx4 v[76:79], v30, s[0:1]
	v_mul_f32_e32 v10, v10, v53
	v_mul_f32_e32 v17, v20, v53
	v_mul_f32_e32 v15, v15, v53
	v_mul_f32_e32 v13, v13, v53
	v_mul_f32_e32 v12, v12, v53
	v_mul_f32_e32 v11, v11, v53
	v_mul_f32_e32 v55, v26, v53
	s_waitcnt vmcnt(1)
	v_fmac_f32_e32 v75, v59, v10
	v_cvt_pk_bf16_f32 v10, v75, s0
	ds_write_b16 v54, v10 offset:1904
	v_mul_f32_e32 v10, v25, v53
	v_fma_f32 v6, v6, v10, v68
	v_cvt_pk_bf16_f32 v6, v6, s0
	ds_write_b16 v54, v6 offset:2176
	v_mul_f32_e32 v6, v24, v53
	v_fma_f32 v6, v7, v6, v69
	v_cvt_pk_bf16_f32 v6, v6, s0
	ds_write_b16 v54, v6 offset:2448
	v_mul_f32_e32 v6, v23, v53
	v_fma_f32 v6, v8, v6, v70
	v_cvt_pk_bf16_f32 v6, v6, s0
	ds_write_b16 v54, v6 offset:2720
	v_mul_f32_e32 v6, v22, v53
	v_fmac_f32_e32 v71, v9, v6
	v_cvt_pk_bf16_f32 v6, v71, s0
	ds_write_b16 v54, v6 offset:2992
	v_mul_f32_e32 v6, v21, v53
	v_fma_f32 v2, v2, v6, v64
	v_cvt_pk_bf16_f32 v2, v2, s0
	ds_write_b16 v54, v2 offset:3264
	v_mul_f32_e32 v2, v19, v53
	v_fma_f32 v2, v3, v2, v65
	v_cvt_pk_bf16_f32 v2, v2, s0
	ds_write_b16 v54, v2 offset:3536
	v_mul_f32_e32 v2, v16, v53
	s_waitcnt vmcnt(0)
	v_fma_f32 v17, v61, v17, v77
	v_fma_f32 v2, v4, v2, v66
	v_cvt_pk_bf16_f32 v17, v17, s0
	v_cvt_pk_bf16_f32 v2, v2, s0
	ds_write_b16 v54, v17 offset:272
	v_mul_f32_e32 v17, v18, v53
	ds_write_b16 v54, v2 offset:3808
	v_mul_f32_e32 v2, v14, v53
	v_fma_f32 v28, v60, v28, v76
	v_fma_f32 v17, v62, v17, v78
	v_fmac_f32_e32 v79, v63, v15
	v_fma_f32 v13, v56, v13, v72
	v_fma_f32 v12, v57, v12, v73
	v_fma_f32 v11, v58, v11, v74
	v_fmac_f32_e32 v67, v5, v2
	v_cvt_pk_bf16_f32 v28, v28, s0
	v_cvt_pk_bf16_f32 v17, v17, s0
	v_cvt_pk_bf16_f32 v15, v79, s0
	v_cvt_pk_bf16_f32 v13, v13, s0
	v_cvt_pk_bf16_f32 v12, v12, s0
	v_cvt_pk_bf16_f32 v11, v11, s0
	v_cvt_pk_bf16_f32 v2, v67, s0
	ds_write_b16 v54, v28
	ds_write_b16 v54, v17 offset:544
	ds_write_b16 v54, v15 offset:816
	ds_write_b16 v54, v13 offset:1088
	ds_write_b16 v54, v12 offset:1360
	ds_write_b16 v54, v11 offset:1632
	ds_write_b16 v54, v2 offset:4080
	global_load_dwordx4 v[2:5], v30, s[40:41] offset:112
	global_load_dwordx4 v[6:9], v30, s[40:41] offset:96
	global_load_dwordx4 v[10:13], v30, s[40:41] offset:80
	global_load_dwordx4 v[26:29], v30, s[40:41] offset:64
	global_load_dwordx4 v[14:17], v30, s[0:1] offset:112
	global_load_dwordx4 v[18:21], v30, s[0:1] offset:96
	global_load_dwordx4 v[22:25], v30, s[0:1] offset:80
	s_nop 0
	global_load_dwordx4 v[30:33], v30, s[0:1] offset:64
	s_waitcnt vmcnt(0)
	v_fma_f32 v26, v26, v55, v30
	v_cvt_pk_bf16_f32 v26, v26, s0
	ds_write_b16 v54, v26 offset:4352
	v_mul_f32_e32 v26, v52, v53
	v_fma_f32 v26, v27, v26, v31
	v_cvt_pk_bf16_f32 v26, v26, s0
	ds_write_b16 v54, v26 offset:4624
	v_mul_f32_e32 v26, v51, v53
	v_fma_f32 v26, v28, v26, v32
	v_cvt_pk_bf16_f32 v26, v26, s0
	ds_write_b16 v54, v26 offset:4896
	v_mul_f32_e32 v26, v50, v53
	v_fmac_f32_e32 v33, v29, v26
	v_cvt_pk_bf16_f32 v26, v33, s0
	ds_write_b16 v54, v26 offset:5168
	v_mul_f32_e32 v26, v49, v53
	v_fma_f32 v10, v10, v26, v22
	v_cvt_pk_bf16_f32 v10, v10, s0
	ds_write_b16 v54, v10 offset:5440
	v_mul_f32_e32 v10, v48, v53
	v_fma_f32 v10, v11, v10, v23
	v_cvt_pk_bf16_f32 v10, v10, s0
	ds_write_b16 v54, v10 offset:5712
	v_mul_f32_e32 v10, v44, v53
	v_fma_f32 v10, v12, v10, v24
	v_cvt_pk_bf16_f32 v10, v10, s0
	ds_write_b16 v54, v10 offset:5984
	v_mul_f32_e32 v10, v45, v53
	v_fmac_f32_e32 v25, v13, v10
	v_cvt_pk_bf16_f32 v10, v25, s0
	ds_write_b16 v54, v10 offset:6256
	v_mul_f32_e32 v10, v42, v53
	v_fma_f32 v6, v6, v10, v18
	v_cvt_pk_bf16_f32 v6, v6, s0
	ds_write_b16 v54, v6 offset:6528
	v_mul_f32_e32 v6, v43, v53
	v_fma_f32 v6, v6, v7, v19
	v_cvt_pk_bf16_f32 v6, v6, s0
	ds_write_b16 v54, v6 offset:6800
	v_mul_f32_e32 v6, v40, v53
	v_fma_f32 v6, v6, v8, v20
	v_cvt_pk_bf16_f32 v6, v6, s0
	ds_write_b16 v54, v6 offset:7072
	v_mul_f32_e32 v6, v41, v53
	v_fmac_f32_e32 v21, v6, v9
	v_cvt_pk_bf16_f32 v6, v21, s0
	ds_write_b16 v54, v6 offset:7344
	v_mul_f32_e32 v6, v38, v53
	v_fma_f32 v2, v6, v2, v14
	v_cvt_pk_bf16_f32 v2, v2, s0
	ds_write_b16 v54, v2 offset:7616
	v_mul_f32_e32 v2, v39, v53
	v_fma_f32 v2, v2, v3, v15
	v_cvt_pk_bf16_f32 v2, v2, s0
	ds_write_b16 v54, v2 offset:7888
	v_mul_f32_e32 v2, v36, v53
	v_fma_f32 v2, v2, v4, v16
	v_cvt_pk_bf16_f32 v2, v2, s0
	ds_write_b16 v54, v2 offset:8160
	v_mul_f32_e32 v2, v37, v53
	v_fmac_f32_e32 v17, v2, v5
	v_cvt_pk_bf16_f32 v2, v17, s0
	v_readlane_b32 s0, v246, 29
	s_or_b32 s0, s13, s0
	s_ashr_i32 s1, s0, 31
	s_lshl_b64 s[40:41], s[0:1], 15
	v_bfe_u32 v44, v47, 4, 2
	s_add_u32 s40, s42, s40
	ds_write_b16 v54, v2 offset:8432
	s_addc_u32 s41, s43, s41
	v_lshlrev_b32_e32 v2, 4, v44
	v_mov_b32_e32 v3, v0
	v_lshl_add_u64 v[32:33], s[40:41], 0, v[2:3]
	v_mul_u32_u24_e32 v3, 0x110, v46
	v_add3_u32 v45, 0, v2, v3
	v_lshlrev_b32_e32 v2, 7, v46
	v_lshl_or_b32 v40, v1, 12, v2
	v_ashrrev_i32_e32 v41, 31, v40
	v_lshl_add_u64 v[2:3], v[40:41], 1, v[32:33]
	v_or_b32_e32 v40, 0x800, v40
	v_ashrrev_i32_e32 v41, 31, v40
	s_waitcnt lgkmcnt(0)
	s_barrier
	v_lshl_add_u64 v[32:33], v[40:41], 1, v[32:33]
	ds_read_b128 v[4:7], v45
	ds_read_b128 v[8:11], v45 offset:4352
	ds_read_b128 v[12:15], v45 offset:8704
	ds_read_b128 v[16:19], v45 offset:13056
	global_load_dwordx4 v[20:23], v[2:3], off
	global_load_dwordx4 v[40:43], v[32:33], off
	global_load_dwordx4 v[72:75], v[2:3], off offset:64
	global_load_dwordx4 v[76:79], v[32:33], off offset:64
	global_load_dwordx4 v[80:83], v[2:3], off offset:128
	global_load_dwordx4 v[84:87], v[32:33], off offset:128
	global_load_dwordx4 v[88:91], v[2:3], off offset:192
	s_waitcnt vmcnt(6) lgkmcnt(3)
	v_mfma_f32_16x16x32_bf16 v[24:27], v[4:7], v[20:23], 0
	v_lshl_or_b32 v1, v1, 5, v46
	s_waitcnt lgkmcnt(2)
	v_mfma_f32_16x16x32_bf16 v[28:31], v[8:11], v[20:23], 0
	s_waitcnt lgkmcnt(1)
	v_mfma_f32_16x16x32_bf16 v[36:39], v[12:15], v[20:23], 0
	s_waitcnt lgkmcnt(0)
	v_mfma_f32_16x16x32_bf16 v[20:23], v[16:19], v[20:23], 0
	s_waitcnt vmcnt(5)
	v_mfma_f32_16x16x32_bf16 v[4:7], v[4:7], v[40:43], 0
	v_mfma_f32_16x16x32_bf16 v[8:11], v[8:11], v[40:43], 0
	v_mfma_f32_16x16x32_bf16 v[12:15], v[12:15], v[40:43], 0
	v_mfma_f32_16x16x32_bf16 v[16:19], v[16:19], v[40:43], 0
	ds_read_b128 v[40:43], v45 offset:64
	ds_read_b128 v[48:51], v45 offset:4416
	ds_read_b128 v[52:55], v45 offset:8768
	ds_read_b128 v[56:59], v45 offset:13120
	s_waitcnt vmcnt(4) lgkmcnt(3)
	v_mfma_f32_16x16x32_bf16 v[24:27], v[40:43], v[72:75], v[24:27]
	s_waitcnt lgkmcnt(2)
	v_mfma_f32_16x16x32_bf16 v[28:31], v[48:51], v[72:75], v[28:31]
	s_waitcnt lgkmcnt(1)
	v_mfma_f32_16x16x32_bf16 v[36:39], v[52:55], v[72:75], v[36:39]
	s_waitcnt lgkmcnt(0)
	v_mfma_f32_16x16x32_bf16 v[20:23], v[56:59], v[72:75], v[20:23]
	s_waitcnt vmcnt(3)
	v_mfma_f32_16x16x32_bf16 v[4:7], v[40:43], v[76:79], v[4:7]
	v_mfma_f32_16x16x32_bf16 v[8:11], v[48:51], v[76:79], v[8:11]
	v_mfma_f32_16x16x32_bf16 v[12:15], v[52:55], v[76:79], v[12:15]
	v_mfma_f32_16x16x32_bf16 v[16:19], v[56:59], v[76:79], v[16:19]
	ds_read_b128 v[40:43], v45 offset:128
	ds_read_b128 v[48:51], v45 offset:4480
	ds_read_b128 v[52:55], v45 offset:8832
	ds_read_b128 v[56:59], v45 offset:13184
	s_waitcnt vmcnt(2) lgkmcnt(3)
	v_mfma_f32_16x16x32_bf16 v[24:27], v[40:43], v[80:83], v[24:27]
	s_waitcnt lgkmcnt(2)
	v_mfma_f32_16x16x32_bf16 v[28:31], v[48:51], v[80:83], v[28:31]
	s_waitcnt lgkmcnt(1)
	v_mfma_f32_16x16x32_bf16 v[36:39], v[52:55], v[80:83], v[36:39]
	s_waitcnt lgkmcnt(0)
	v_mfma_f32_16x16x32_bf16 v[60:63], v[56:59], v[80:83], v[20:23]
	s_nop 2
	s_waitcnt vmcnt(1)
	v_mfma_f32_16x16x32_bf16 v[4:7], v[40:43], v[84:87], v[4:7]
	v_mfma_f32_16x16x32_bf16 v[8:11], v[48:51], v[84:87], v[8:11]
	v_mfma_f32_16x16x32_bf16 v[40:43], v[52:55], v[84:87], v[12:15]
	v_mfma_f32_16x16x32_bf16 v[48:51], v[56:59], v[84:87], v[16:19]
	s_nop 1
	ds_read_b128 v[12:15], v45 offset:192
	ds_read_b128 v[52:55], v45 offset:4544
	ds_read_b128 v[56:59], v45 offset:8896
	ds_read_b128 v[64:67], v45 offset:13248
	s_waitcnt vmcnt(0) lgkmcnt(3)
	v_mfma_f32_16x16x32_bf16 v[68:71], v[12:15], v[88:91], v[24:27]
	s_waitcnt lgkmcnt(2)
	v_mfma_f32_16x16x32_bf16 v[26:29], v[52:55], v[88:91], v[28:31]
	s_nop 2
	global_load_dwordx4 v[30:33], v[32:33], off offset:192
	s_waitcnt lgkmcnt(1)
	v_mfma_f32_16x16x32_bf16 v[22:25], v[56:59], v[88:91], v[36:39]
	s_waitcnt lgkmcnt(0)
	v_mfma_f32_16x16x32_bf16 v[18:21], v[64:67], v[88:91], v[60:63]
	s_waitcnt vmcnt(0)
	v_mfma_f32_16x16x32_bf16 v[14:17], v[12:15], v[30:33], v[4:7]
	v_mfma_f32_16x16x32_bf16 v[10:13], v[52:55], v[30:33], v[8:11]
	v_mfma_f32_16x16x32_bf16 v[6:9], v[56:59], v[30:33], v[40:43]
	v_mfma_f32_16x16x32_bf16 v[2:5], v[64:67], v[30:33], v[48:51]
	v_lshl_add_u32 v30, s0, 7, v1
	v_ashrrev_i32_e32 v31, 31, v30
	v_add_u32_e32 v1, s12, v1
	v_lshl_add_u64 v[32:33], v[30:31], 2, s[74:75]
	v_mad_i64_i32 v[38:39], s[0:1], v1, s9, v[34:35]
	v_lshl_or_b32 v30, v44, 3, s2
	v_mov_b32_e32 v31, v0
	v_lshl_add_u64 v[38:39], v[38:39], 0, v[30:31]
	global_load_dword v36, v[32:33], off
	global_load_dwordx2 v[40:41], v[38:39], off offset:2560
	global_load_dwordx2 v[42:43], v[38:39], off offset:3584
	s_mov_b32 s52, 0x18200
	s_mov_b32 s53, 0
	v_lshl_add_u64 v[72:73], s[52:53], 0, v[38:39]
	global_load_dword v242, v[32:33], off offset:64
	global_load_dwordx2 v[152:153], v[38:39], off offset:2592
	global_load_dwordx2 v[154:155], v[38:39], off offset:3616
	global_load_dwordx2 v[156:157], v[38:39], off offset:2624
	global_load_dwordx2 v[158:159], v[38:39], off offset:3648
	global_load_dwordx2 v[160:161], v[38:39], off offset:2656
	global_load_dwordx2 v[162:163], v[38:39], off offset:3680
	global_load_dwordx2 v[164:165], v[72:73], off offset:2560
	global_load_dwordx2 v[166:167], v[72:73], off offset:3584
	global_load_dwordx2 v[168:169], v[72:73], off offset:2592
	global_load_dwordx2 v[170:171], v[72:73], off offset:3616
	global_load_dwordx2 v[234:235], v[72:73], off offset:2624
	global_load_dwordx2 v[236:237], v[72:73], off offset:3648
	global_load_dwordx2 v[238:239], v[72:73], off offset:2656
	global_load_dwordx2 v[240:241], v[72:73], off offset:3680
	v_or_b32_e32 v1, 16, v1
	v_readlane_b32 s64, v247, 53
	v_readlane_b32 s72, v247, 61
	v_readlane_b32 s65, v247, 54
	v_readlane_b32 s66, v247, 55
	v_readlane_b32 s67, v247, 56
	v_readlane_b32 s68, v247, 57
	v_readlane_b32 s69, v247, 58
	v_readlane_b32 s70, v247, 59
	v_readlane_b32 s71, v247, 60
	v_readlane_b32 s73, v247, 62
	v_readlane_b32 s74, v247, 63
	v_readlane_b32 s75, v246, 0
	v_readlane_b32 s76, v246, 1
	v_readlane_b32 s77, v246, 2
	v_readlane_b32 s78, v246, 3
	v_readlane_b32 s79, v246, 4
	v_readlane_b32 s72, v246, 60
	s_waitcnt vmcnt(0)
	v_and_b32_e32 v49, 0xffff0000, v40
	v_lshlrev_b32_e32 v44, 16, v42
	v_mul_f32_e32 v37, 0xbfb8aa3b, v44
	v_exp_f32_e32 v37, v37
	v_and_b32_e32 v45, 0xffff0000, v42
	v_lshlrev_b32_e32 v48, 16, v40
	v_add_f32_e32 v37, 1.0, v37
	v_rcp_f32_e32 v46, v37
	v_pk_add_f32 v[50:51], v[68:69], v[36:37] op_sel_hi:[1,0]
	v_mul_f32_e32 v37, 0xbfb8aa3b, v45
	v_exp_f32_e32 v37, v37
	v_pk_mul_f32 v[48:49], v[50:51], v[48:49]
	v_add_f32_e32 v37, 1.0, v37
	v_rcp_f32_e32 v47, v37
	s_nop 0
	v_pk_mul_f32 v[44:45], v[46:47], v[44:45]
	s_nop 0
	v_pk_mul_f32 v[44:45], v[48:49], v[44:45]
	v_and_b32_e32 v47, 0xffff0000, v41
	v_cvt_pk_bf16_f32 v40, v44, v45
	v_lshlrev_b32_e32 v44, 16, v43
	v_mul_f32_e32 v37, 0xbfb8aa3b, v44
	v_exp_f32_e32 v37, v37
	v_and_b32_e32 v45, 0xffff0000, v43
	v_lshlrev_b32_e32 v46, 16, v41
	v_add_f32_e32 v37, 1.0, v37
	v_rcp_f32_e32 v42, v37
	v_pk_add_f32 v[48:49], v[70:71], v[36:37] op_sel_hi:[1,0]
	v_mul_f32_e32 v37, 0xbfb8aa3b, v45
	v_exp_f32_e32 v37, v37
	v_pk_mul_f32 v[46:47], v[48:49], v[46:47]
	v_add_f32_e32 v37, 1.0, v37
	v_rcp_f32_e32 v43, v37
	s_nop 0
	v_pk_mul_f32 v[42:43], v[42:43], v[44:45]
	s_nop 0
	v_pk_mul_f32 v[42:43], v[46:47], v[42:43]
	s_nop 0
	v_cvt_pk_bf16_f32 v41, v42, v43
	global_store_dwordx2 v[38:39], v[40:41], off offset:2560
	v_mov_b32_e32 v40, v152
	v_mov_b32_e32 v41, v153
	s_nop 0
	v_mov_b32_e32 v42, v154
	v_mov_b32_e32 v43, v155
	v_and_b32_e32 v49, 0xffff0000, v40
	v_lshlrev_b32_e32 v44, 16, v42
	v_mul_f32_e32 v37, 0xbfb8aa3b, v44
	v_exp_f32_e32 v37, v37
	v_and_b32_e32 v45, 0xffff0000, v42
	v_lshlrev_b32_e32 v48, 16, v40
	v_lshlrev_b32_e32 v42, 16, v41
	v_add_f32_e32 v37, 1.0, v37
	v_rcp_f32_e32 v46, v37
	v_pk_add_f32 v[26:27], v[26:27], v[36:37] op_sel_hi:[1,0]
	v_mul_f32_e32 v37, 0xbfb8aa3b, v45
	v_exp_f32_e32 v37, v37
	v_pk_mul_f32 v[26:27], v[26:27], v[48:49]
	v_add_f32_e32 v37, 1.0, v37
	v_rcp_f32_e32 v47, v37
	v_pk_add_f32 v[28:29], v[28:29], v[36:37] op_sel_hi:[1,0]
	v_pk_add_f32 v[22:23], v[22:23], v[36:37] op_sel_hi:[1,0]
	v_pk_add_f32 v[24:25], v[24:25], v[36:37] op_sel_hi:[1,0]
	v_pk_mul_f32 v[44:45], v[46:47], v[44:45]
	v_pk_add_f32 v[18:19], v[18:19], v[36:37] op_sel_hi:[1,0]
	v_pk_mul_f32 v[26:27], v[26:27], v[44:45]
	v_lshlrev_b32_e32 v44, 16, v43
	v_cvt_pk_bf16_f32 v26, v26, v27
	v_mul_f32_e32 v27, 0xbfb8aa3b, v44
	v_exp_f32_e32 v27, v27
	v_and_b32_e32 v45, 0xffff0000, v43
	v_and_b32_e32 v43, 0xffff0000, v41
	v_pk_mul_f32 v[28:29], v[28:29], v[42:43]
	v_add_f32_e32 v27, 1.0, v27
	v_rcp_f32_e32 v40, v27
	v_mul_f32_e32 v27, 0xbfb8aa3b, v45
	v_exp_f32_e32 v27, v27
	v_pk_add_f32 v[20:21], v[20:21], v[36:37] op_sel_hi:[1,0]
	v_add_f32_e32 v27, 1.0, v27
	v_rcp_f32_e32 v41, v27
	s_nop 0
	v_pk_mul_f32 v[40:41], v[40:41], v[44:45]
	s_nop 0
	v_pk_mul_f32 v[28:29], v[28:29], v[40:41]
	s_nop 0
	v_cvt_pk_bf16_f32 v27, v28, v29
	global_store_dwordx2 v[38:39], v[26:27], off offset:2592
	v_mov_b32_e32 v26, v156
	v_mov_b32_e32 v27, v157
	s_nop 0
	v_mov_b32_e32 v28, v158
	v_mov_b32_e32 v29, v159
	v_and_b32_e32 v45, 0xffff0000, v26
	v_and_b32_e32 v41, 0xffff0000, v28
	v_lshlrev_b32_e32 v40, 16, v28
	v_mul_f32_e32 v28, 0xbfb8aa3b, v40
	v_lshlrev_b32_e32 v44, 16, v26
	v_mul_f32_e32 v26, 0xbfb8aa3b, v41
	v_exp_f32_e32 v28, v28
	v_exp_f32_e32 v26, v26
	v_pk_mul_f32 v[22:23], v[22:23], v[44:45]
	v_add_f32_e32 v28, 1.0, v28
	v_add_f32_e32 v26, 1.0, v26
	v_rcp_f32_e32 v42, v28
	v_rcp_f32_e32 v43, v26
	v_lshlrev_b32_e32 v28, 16, v27
	v_pk_mul_f32 v[40:41], v[42:43], v[40:41]
	s_nop 0
	v_pk_mul_f32 v[22:23], v[22:23], v[40:41]
	v_lshlrev_b32_e32 v40, 16, v29
	v_cvt_pk_bf16_f32 v22, v22, v23
	v_mul_f32_e32 v23, 0xbfb8aa3b, v40
	v_exp_f32_e32 v23, v23
	v_and_b32_e32 v41, 0xffff0000, v29
	v_and_b32_e32 v29, 0xffff0000, v27
	v_pk_mul_f32 v[24:25], v[24:25], v[28:29]
	v_add_f32_e32 v23, 1.0, v23
	v_rcp_f32_e32 v26, v23
	v_mul_f32_e32 v23, 0xbfb8aa3b, v41
	v_exp_f32_e32 v23, v23
	s_nop 0
	v_add_f32_e32 v23, 1.0, v23
	v_rcp_f32_e32 v27, v23
	s_nop 0
	v_pk_mul_f32 v[26:27], v[26:27], v[40:41]
	s_nop 0
	v_pk_mul_f32 v[24:25], v[24:25], v[26:27]
	s_nop 0
	v_cvt_pk_bf16_f32 v23, v24, v25
	global_store_dwordx2 v[38:39], v[22:23], off offset:2624
	v_mov_b32_e32 v22, v160
	v_mov_b32_e32 v23, v161
	s_nop 0
	v_mov_b32_e32 v24, v162
	v_mov_b32_e32 v25, v163
	v_and_b32_e32 v41, 0xffff0000, v22
	v_and_b32_e32 v27, 0xffff0000, v24
	v_lshlrev_b32_e32 v26, 16, v24
	v_mul_f32_e32 v24, 0xbfb8aa3b, v26
	v_lshlrev_b32_e32 v40, 16, v22
	v_mul_f32_e32 v22, 0xbfb8aa3b, v27
	v_exp_f32_e32 v24, v24
	v_exp_f32_e32 v22, v22
	v_pk_mul_f32 v[18:19], v[18:19], v[40:41]
	v_add_f32_e32 v24, 1.0, v24
	v_add_f32_e32 v22, 1.0, v22
	v_rcp_f32_e32 v28, v24
	v_rcp_f32_e32 v29, v22
	v_lshlrev_b32_e32 v24, 16, v23
	v_pk_mul_f32 v[26:27], v[28:29], v[26:27]
	s_nop 0
	v_pk_mul_f32 v[18:19], v[18:19], v[26:27]
	v_lshlrev_b32_e32 v26, 16, v25
	v_cvt_pk_bf16_f32 v18, v18, v19
	v_mul_f32_e32 v19, 0xbfb8aa3b, v26
	v_exp_f32_e32 v19, v19
	v_and_b32_e32 v27, 0xffff0000, v25
	v_and_b32_e32 v25, 0xffff0000, v23
	v_pk_mul_f32 v[20:21], v[20:21], v[24:25]
	v_add_f32_e32 v19, 1.0, v19
	v_rcp_f32_e32 v22, v19
	v_mul_f32_e32 v19, 0xbfb8aa3b, v27
	v_exp_f32_e32 v19, v19
	s_nop 0
	v_add_f32_e32 v19, 1.0, v19
	v_rcp_f32_e32 v23, v19
	s_nop 0
	v_pk_mul_f32 v[22:23], v[22:23], v[26:27]
	s_nop 0
	v_pk_mul_f32 v[20:21], v[20:21], v[22:23]
	s_nop 0
	v_cvt_pk_bf16_f32 v19, v20, v21
	v_mad_i64_i32 v[20:21], s[0:1], v1, s9, v[34:35]
	global_store_dwordx2 v[38:39], v[18:19], off offset:2656
	v_lshl_add_u64 v[20:21], v[20:21], 0, v[30:31]
	v_mov_b32_e32 v18, v242
	v_mov_b32_e32 v22, v164
	v_mov_b32_e32 v23, v165
	v_mov_b32_e32 v24, v166
	v_mov_b32_e32 v25, v167
	s_mov_b64 s[0:1], 0
	v_and_b32_e32 v31, 0xffff0000, v22
	v_lshlrev_b32_e32 v26, 16, v24
	v_mul_f32_e32 v1, 0xbfb8aa3b, v26
	v_exp_f32_e32 v1, v1
	v_and_b32_e32 v27, 0xffff0000, v24
	v_lshlrev_b32_e32 v30, 16, v22
	v_pk_add_f32 v[14:15], v[14:15], v[18:19] op_sel_hi:[1,0]
	v_add_f32_e32 v1, 1.0, v1
	v_rcp_f32_e32 v28, v1
	v_mul_f32_e32 v1, 0xbfb8aa3b, v27
	v_exp_f32_e32 v1, v1
	v_pk_mul_f32 v[14:15], v[14:15], v[30:31]
	v_lshlrev_b32_e32 v24, 16, v23
	v_pk_add_f32 v[16:17], v[16:17], v[18:19] op_sel_hi:[1,0]
	v_add_f32_e32 v1, 1.0, v1
	v_rcp_f32_e32 v29, v1
	v_pk_add_f32 v[10:11], v[10:11], v[18:19] op_sel_hi:[1,0]
	v_pk_add_f32 v[12:13], v[12:13], v[18:19] op_sel_hi:[1,0]
	v_pk_add_f32 v[6:7], v[6:7], v[18:19] op_sel_hi:[1,0]
	v_pk_mul_f32 v[26:27], v[28:29], v[26:27]
	v_pk_add_f32 v[8:9], v[8:9], v[18:19] op_sel_hi:[1,0]
	v_pk_mul_f32 v[14:15], v[14:15], v[26:27]
	v_lshlrev_b32_e32 v26, 16, v25
	v_mul_f32_e32 v1, 0xbfb8aa3b, v26
	v_exp_f32_e32 v1, v1
	v_and_b32_e32 v27, 0xffff0000, v25
	v_and_b32_e32 v25, 0xffff0000, v23
	v_pk_mul_f32 v[16:17], v[16:17], v[24:25]
	v_add_f32_e32 v1, 1.0, v1
	v_rcp_f32_e32 v22, v1
	v_mul_f32_e32 v1, 0xbfb8aa3b, v27
	v_exp_f32_e32 v1, v1
	v_cvt_pk_bf16_f32 v14, v14, v15
	v_pk_add_f32 v[2:3], v[2:3], v[18:19] op_sel_hi:[1,0]
	v_pk_add_f32 v[4:5], v[4:5], v[18:19] op_sel_hi:[1,0]
	v_add_f32_e32 v1, 1.0, v1
	v_rcp_f32_e32 v23, v1
	s_nop 0
	v_pk_mul_f32 v[22:23], v[22:23], v[26:27]
	s_nop 0
	v_pk_mul_f32 v[16:17], v[16:17], v[22:23]
	s_nop 0
	v_cvt_pk_bf16_f32 v15, v16, v17
	global_store_dwordx2 v[20:21], v[14:15], off offset:2560
	v_mov_b32_e32 v14, v168
	v_mov_b32_e32 v15, v169
	s_nop 0
	v_mov_b32_e32 v16, v170
	v_mov_b32_e32 v17, v171
	v_and_b32_e32 v27, 0xffff0000, v14
	v_lshlrev_b32_e32 v22, 16, v16
	v_mul_f32_e32 v1, 0xbfb8aa3b, v22
	v_exp_f32_e32 v1, v1
	v_and_b32_e32 v23, 0xffff0000, v16
	v_lshlrev_b32_e32 v26, 16, v14
	v_pk_mul_f32 v[10:11], v[10:11], v[26:27]
	v_add_f32_e32 v1, 1.0, v1
	v_rcp_f32_e32 v24, v1
	v_mul_f32_e32 v1, 0xbfb8aa3b, v23
	v_exp_f32_e32 v1, v1
	v_lshlrev_b32_e32 v16, 16, v15
	v_add_f32_e32 v1, 1.0, v1
	v_rcp_f32_e32 v25, v1
	s_nop 0
	v_pk_mul_f32 v[22:23], v[24:25], v[22:23]
	s_nop 0
	v_pk_mul_f32 v[10:11], v[10:11], v[22:23]
	v_lshlrev_b32_e32 v22, 16, v17
	v_mul_f32_e32 v1, 0xbfb8aa3b, v22
	v_exp_f32_e32 v1, v1
	v_and_b32_e32 v23, 0xffff0000, v17
	v_and_b32_e32 v17, 0xffff0000, v15
	v_pk_mul_f32 v[12:13], v[12:13], v[16:17]
	v_add_f32_e32 v1, 1.0, v1
	v_rcp_f32_e32 v14, v1
	v_mul_f32_e32 v1, 0xbfb8aa3b, v23
	v_exp_f32_e32 v1, v1
	v_cvt_pk_bf16_f32 v10, v10, v11
	v_add_f32_e32 v1, 1.0, v1
	v_rcp_f32_e32 v15, v1
	s_nop 0
	v_pk_mul_f32 v[14:15], v[14:15], v[22:23]
	s_nop 0
	v_pk_mul_f32 v[12:13], v[12:13], v[14:15]
	s_nop 0
	v_cvt_pk_bf16_f32 v11, v12, v13
	global_store_dwordx2 v[20:21], v[10:11], off offset:2592
	v_mov_b32_e32 v10, v234
	v_mov_b32_e32 v11, v235
	s_nop 0
	v_mov_b32_e32 v12, v236
	v_mov_b32_e32 v13, v237
	v_and_b32_e32 v23, 0xffff0000, v10
	v_lshlrev_b32_e32 v14, 16, v12
	v_mul_f32_e32 v1, 0xbfb8aa3b, v14
	v_exp_f32_e32 v1, v1
	v_and_b32_e32 v15, 0xffff0000, v12
	v_lshlrev_b32_e32 v22, 16, v10
	v_pk_mul_f32 v[6:7], v[6:7], v[22:23]
	v_add_f32_e32 v1, 1.0, v1
	v_rcp_f32_e32 v16, v1
	v_mul_f32_e32 v1, 0xbfb8aa3b, v15
	v_exp_f32_e32 v1, v1
	v_lshlrev_b32_e32 v12, 16, v11
	v_add_f32_e32 v1, 1.0, v1
	v_rcp_f32_e32 v17, v1
	s_nop 0
	v_pk_mul_f32 v[14:15], v[16:17], v[14:15]
	s_nop 0
	v_pk_mul_f32 v[6:7], v[6:7], v[14:15]
	v_lshlrev_b32_e32 v14, 16, v13
	v_mul_f32_e32 v1, 0xbfb8aa3b, v14
	v_exp_f32_e32 v1, v1
	v_and_b32_e32 v15, 0xffff0000, v13
	v_and_b32_e32 v13, 0xffff0000, v11
	v_pk_mul_f32 v[8:9], v[8:9], v[12:13]
	v_add_f32_e32 v1, 1.0, v1
	v_rcp_f32_e32 v10, v1
	v_mul_f32_e32 v1, 0xbfb8aa3b, v15
	v_exp_f32_e32 v1, v1
	v_cvt_pk_bf16_f32 v6, v6, v7
	v_add_f32_e32 v1, 1.0, v1
	v_rcp_f32_e32 v11, v1
	s_nop 0
	v_pk_mul_f32 v[10:11], v[10:11], v[14:15]
	s_nop 0
	v_pk_mul_f32 v[8:9], v[8:9], v[10:11]
	s_nop 0
	v_cvt_pk_bf16_f32 v7, v8, v9
	global_store_dwordx2 v[20:21], v[6:7], off offset:2624
	v_mov_b32_e32 v6, v238
	v_mov_b32_e32 v7, v239
	s_nop 0
	v_mov_b32_e32 v8, v240
	v_mov_b32_e32 v9, v241
	v_and_b32_e32 v15, 0xffff0000, v6
	v_lshlrev_b32_e32 v10, 16, v8
	v_mul_f32_e32 v1, 0xbfb8aa3b, v10
	v_exp_f32_e32 v1, v1
	v_and_b32_e32 v11, 0xffff0000, v8
	v_lshlrev_b32_e32 v14, 16, v6
	v_pk_mul_f32 v[2:3], v[2:3], v[14:15]
	v_add_f32_e32 v1, 1.0, v1
	v_rcp_f32_e32 v12, v1
	v_mul_f32_e32 v1, 0xbfb8aa3b, v11
	v_exp_f32_e32 v1, v1
	v_lshlrev_b32_e32 v8, 16, v7
	v_add_f32_e32 v1, 1.0, v1
	v_rcp_f32_e32 v13, v1
	s_nop 0
	v_pk_mul_f32 v[10:11], v[12:13], v[10:11]
	s_nop 0
	v_pk_mul_f32 v[2:3], v[2:3], v[10:11]
	v_lshlrev_b32_e32 v10, 16, v9
	v_mul_f32_e32 v1, 0xbfb8aa3b, v10
	v_exp_f32_e32 v1, v1
	v_and_b32_e32 v11, 0xffff0000, v9
	v_and_b32_e32 v9, 0xffff0000, v7
	v_pk_mul_f32 v[4:5], v[4:5], v[8:9]
	v_add_f32_e32 v1, 1.0, v1
	v_rcp_f32_e32 v6, v1
	v_mul_f32_e32 v1, 0xbfb8aa3b, v11
	v_exp_f32_e32 v1, v1
	v_cvt_pk_bf16_f32 v2, v2, v3
	v_add_f32_e32 v1, 1.0, v1
	v_rcp_f32_e32 v7, v1
	s_nop 0
	v_pk_mul_f32 v[6:7], v[6:7], v[10:11]
	s_nop 0
	v_pk_mul_f32 v[4:5], v[4:5], v[6:7]
	s_nop 0
	v_cvt_pk_bf16_f32 v3, v4, v5
	global_store_dwordx2 v[20:21], v[2:3], off offset:2656

	.amdhsa_kernel _Z4mega1Piii
		.amdhsa_group_segment_fixed_size 0
		.amdhsa_private_segment_fixed_size 0
		.amdhsa_kernarg_size 464
		.amdhsa_user_sgpr_count 2
		.amdhsa_user_sgpr_dispatch_ptr 0
		.amdhsa_user_sgpr_queue_ptr 0
		.amdhsa_user_sgpr_kernarg_segment_ptr 1
		.amdhsa_user_sgpr_dispatch_id 0
		.amdhsa_user_sgpr_kernarg_preload_length 0
		.amdhsa_user_sgpr_kernarg_preload_offset 0
		.amdhsa_user_sgpr_private_segment_size 0
		.amdhsa_uses_dynamic_stack 0
		.amdhsa_enable_private_segment 0
		.amdhsa_system_sgpr_workgroup_id_x 1
		.amdhsa_system_sgpr_workgroup_id_y 0
		.amdhsa_system_sgpr_workgroup_id_z 0
		.amdhsa_system_sgpr_workgroup_info 0
		.amdhsa_system_vgpr_workitem_id 2
		.amdhsa_next_free_vgpr 256
		.amdhsa_next_free_sgpr 100
		.amdhsa_accum_offset 256
		.amdhsa_reserve_vcc 1
		.amdhsa_float_round_mode_32 0
		.amdhsa_float_round_mode_16_64 0
		.amdhsa_float_denorm_mode_32 3
		.amdhsa_float_denorm_mode_16_64 3
		.amdhsa_dx10_clamp 1
		.amdhsa_ieee_mode 1
		.amdhsa_fp16_overflow 0
		.amdhsa_tg_split 0
		.amdhsa_exception_fp_ieee_invalid_op 0
		.amdhsa_exception_fp_denorm_src 0
		.amdhsa_exception_fp_ieee_div_zero 0
		.amdhsa_exception_fp_ieee_overflow 0
		.amdhsa_exception_fp_ieee_underflow 0
		.amdhsa_exception_fp_ieee_inexact 0
		.amdhsa_exception_int_div_zero 0
	.end_amdhsa_kernel

amdhsa.kernels:
  - .agpr_count:     0
    .args:
      - .offset:         0
        .size:           192
        .value_kind:     by_value
      - .offset:         192
        .size:           4
        .value_kind:     by_value
      - .offset:         196
        .size:           4
        .value_kind:     by_value
      - .offset:         200
        .size:           4
        .value_kind:     by_value
      - .offset:         208
        .size:           4
        .value_kind:     hidden_block_count_x
      - .offset:         212
        .size:           4
        .value_kind:     hidden_block_count_y
      - .offset:         216
        .size:           4
        .value_kind:     hidden_block_count_z
      - .offset:         220
        .size:           2
        .value_kind:     hidden_group_size_x
      - .offset:         222
        .size:           2
        .value_kind:     hidden_group_size_y
      - .offset:         224
        .size:           2
        .value_kind:     hidden_group_size_z
      - .offset:         226
        .size:           2
        .value_kind:     hidden_remainder_x
      - .offset:         228
        .size:           2
        .value_kind:     hidden_remainder_y
      - .offset:         230
        .size:           2
        .value_kind:     hidden_remainder_z
      - .offset:         248
        .size:           8
        .value_kind:     hidden_global_offset_x
      - .offset:         256
        .size:           8
        .value_kind:     hidden_global_offset_y
      - .offset:         264
        .size:           8
        .value_kind:     hidden_global_offset_z
      - .offset:         272
        .size:           2
        .value_kind:     hidden_grid_dims
      - .offset:         296
        .size:           8
        .value_kind:     hidden_multigrid_sync_arg
      - .offset:         328
        .size:           4
        .value_kind:     hidden_dynamic_lds_size
    .group_segment_fixed_size: 0
    .kernarg_segment_align: 8
    .kernarg_segment_size: 464
    .language:       OpenCL C
    .language_version:
      - 2
      - 0
    .max_flat_workgroup_size: 256
    .name:           _Z4mega1Piii
    .private_segment_fixed_size: 0
    .sgpr_count:     106
    .sgpr_spill_count: 200
    .symbol:         _Z4mega1Piii.kd
    .uniform_work_group_size: 1
    .uses_dynamic_stack: false
    .vgpr_count:     256
    .vgpr_spill_count: 0
    .wavefront_size: 64
